# v74 + P6 split-K slab prologue DMAs issued before the main epilogue
# baseline (speedup 1.0000x reference)
.LBB0_927:
	s_and_b64 vcc, exec, s[0:1]
	s_cbranch_vccz .Lslab6_skip
	s_cmp_gt_i32 s82, 31
	s_cbranch_scc1 .Lslab6_skip
	v_readfirstlane_b32 s101, v0
	s_lshl_b32 s100, s82, 6
	s_and_b32 s100, s100, 0xffffff00
	s_lshl_b32 s100, s100, 1
	s_lshr_b32 s101, s101, 6
	s_lshl_b32 s101, s101, 10
	s_and_b32 s98, s82, 3
	s_lshl_b32 s98, s98, 20
	s_add_u32 s98, s40, s98
	s_addc_u32 s99, s41, 0
	s_add_u32 s98, s98, s100
	s_addc_u32 s99, s99, 0
	s_add_i32 m0, s101, 0x10000
	s_nop 0
	global_load_lds_dwordx4 v170, s[98:99]
	s_add_i32 m0, s101, 0x12000
	s_nop 0
	global_load_lds_dwordx4 v172, s[98:99]
	s_add_u32 s98, s98, 0x80000
	s_addc_u32 s99, s99, 0
	s_add_i32 m0, s101, 0x14000
	s_nop 0
	global_load_lds_dwordx4 v170, s[98:99]
	s_add_i32 m0, s101, 0x16000
	s_nop 0
	global_load_lds_dwordx4 v172, s[98:99]
	s_add_u32 s98, s94, s100
	s_addc_u32 s99, s95, 0
	s_add_u32 s98, s98, 0xb2d2400
	s_addc_u32 s99, s99, 0
	s_mov_b32 m0, s101
	s_nop 0
	global_load_lds_dwordx4 v170, s[98:99]
	s_add_i32 m0, s101, 0x2000
	s_nop 0
	global_load_lds_dwordx4 v172, s[98:99]
	s_add_u32 s98, s98, 0x80000
	s_addc_u32 s99, s99, 0
	s_add_i32 m0, s101, 0x4000
	s_nop 0
	global_load_lds_dwordx4 v170, s[98:99]
	s_add_i32 m0, s101, 0x6000
	s_nop 0
	global_load_lds_dwordx4 v172, s[98:99]

.LBB0_945:
	s_cmp_gt_i32 s82, 31
	v_readfirstlane_b32 s6, v0
	s_cbranch_scc1 .LBB0_951
	s_lshl_b32 s0, s82, 6
	s_and_b32 s0, s0, 0xffffff00
	s_lshr_b32 s8, s6, 6
	s_and_b32 s7, s82, 3
	s_ashr_i32 s1, s0, 31
	s_lshr_b32 s20, s6, 8
	s_lshl_b32 s19, s8, 10
	s_lshl_b64 s[0:1], s[0:1], 1
	s_lshl_b32 s4, s7, 20
	s_add_u32 s4, s40, s4
	s_addc_u32 s5, s41, 0
	s_add_u32 s4, s4, s0
	s_addc_u32 s5, s5, s1
	s_add_i32 s9, s19, 0
	s_add_i32 m0, s9, 0x10000
	v_mov_b32_e32 v171, 0
	s_add_i32 m0, s9, 0x12000
	s_add_u32 s12, s94, s0
	s_addc_u32 s13, s95, s1
	s_add_u32 s0, s12, 0xb2d2400
	s_addc_u32 s1, s13, 0
	s_mov_b32 m0, s9
	s_add_i32 s18, s9, 0x2000
	s_mov_b32 m0, s18
	s_add_u32 s10, s4, 0x80000
	s_addc_u32 s11, s5, 0
	s_add_i32 m0, s9, 0x14000
	v_mov_b32_e32 v173, v171
	s_add_i32 m0, s9, 0x16000
	s_add_u32 s12, s12, 0xb352400
	s_addc_u32 s13, s13, 0
	s_add_i32 s14, s9, 0x4000
	s_mov_b32 m0, s14
	s_add_i32 s15, s9, 0x6000
	s_mov_b32 m0, s15
	v_lshl_add_u64 v[34:35], s[4:5], 0, v[170:171]
	v_lshl_add_u64 v[36:37], s[4:5], 0, v[172:173]
	v_lshl_add_u64 v[32:33], s[0:1], 0, v[170:171]
	v_lshl_add_u64 v[30:31], s[0:1], 0, v[172:173]
	v_lshl_add_u64 v[28:29], s[10:11], 0, v[170:171]
	v_lshl_add_u64 v[26:27], s[10:11], 0, v[172:173]
	v_lshl_add_u64 v[22:23], s[12:13], 0, v[170:171]
	s_cmp_lg_u32 s20, 1
	v_lshl_add_u64 v[24:25], s[12:13], 0, v[172:173]
	s_cbranch_scc1 .LBB0_948
	s_barrier
